# v28: v26 + P0 weight transposes with both 16-load passes in flight
# baseline (speedup 1.0000x reference)
; #define LAS __attribute__((address_space(3)))
; DI void transpose_item(const float* W, int K, int N, bf16_t* WT, int k0, int n0, int drow0, LAS float* scr, int lane) {
; #pragma unroll 8
;     for (int i = 0; i < 32; ++i) { const int kk = 2 * i + (lane >> 5); scr[kk * 33 + (lane & 31)] = W[(size_t)(k0 + kk) * N + n0 + (lane & 31)]; }
;     asm volatile("s_waitcnt lgkmcnt(0)" ::: "memory");
.LBB0_12:
	s_lshl_b32 s29, s11, 1
	s_lshl_b32 s30, s25, 1
	v_or_b32_e32 v4, s29, v1
	v_or_b32_e32 v19, s30, v2
	s_add_i32 s31, s29, 4
	s_add_i32 s33, s30, 4
	s_add_i32 s34, s29, 8
	s_add_i32 s35, s30, 8
	s_add_i32 s36, s29, 12
	s_add_i32 s37, s30, 12
	s_add_i32 s38, s29, 16
	s_add_i32 s39, s30, 16
	s_add_i32 s40, s29, 20
	s_add_i32 s41, s30, 20
	s_add_i32 s45, s29, 24
	s_add_i32 s47, s30, 24
	s_add_i32 s29, s29, 28
	s_add_i32 s30, s30, 28
	v_add_u32_e32 v22, s10, v19
	v_or_b32_e32 v52, s31, v1
	v_or_b32_e32 v53, s33, v2
	v_or_b32_e32 v54, s34, v1
	v_or_b32_e32 v55, s35, v2
	v_or_b32_e32 v56, s36, v1
	v_or_b32_e32 v57, s37, v2
	v_or_b32_e32 v58, s38, v1
	v_or_b32_e32 v59, s39, v2
	v_or_b32_e32 v60, s40, v1
	v_or_b32_e32 v61, s41, v2
	v_or_b32_e32 v62, s45, v1
	v_or_b32_e32 v63, s47, v2
	v_or_b32_e32 v64, s29, v1
	v_or_b32_e32 v65, s30, v2
	v_add_u32_e32 v20, s22, v4
	v_ashrrev_i32_e32 v23, 31, v22
	v_add_u32_e32 v24, s22, v52
	v_add_u32_e32 v26, s10, v53
	v_add_u32_e32 v28, s22, v54
	v_add_u32_e32 v30, s10, v55
	v_add_u32_e32 v32, s22, v56
	v_add_u32_e32 v34, s10, v57
	v_add_u32_e32 v36, s22, v58
	v_add_u32_e32 v38, s10, v59
	v_add_u32_e32 v40, s22, v60
	v_add_u32_e32 v42, s10, v61
	v_add_u32_e32 v44, s22, v62
	v_add_u32_e32 v46, s10, v63
	v_add_u32_e32 v48, s22, v64
	v_add_u32_e32 v50, s10, v65
	v_ashrrev_i32_e32 v21, 31, v20
	v_lshlrev_b64 v[22:23], 12, v[22:23]
	v_ashrrev_i32_e32 v27, 31, v26
	v_ashrrev_i32_e32 v25, 31, v24
	v_ashrrev_i32_e32 v31, 31, v30
	v_ashrrev_i32_e32 v29, 31, v28
	v_ashrrev_i32_e32 v35, 31, v34
	v_ashrrev_i32_e32 v33, 31, v32
	v_ashrrev_i32_e32 v39, 31, v38
	v_ashrrev_i32_e32 v37, 31, v36
	v_ashrrev_i32_e32 v43, 31, v42
	v_ashrrev_i32_e32 v41, 31, v40
	v_ashrrev_i32_e32 v47, 31, v46
	v_ashrrev_i32_e32 v45, 31, v44
	v_ashrrev_i32_e32 v51, 31, v50
	v_ashrrev_i32_e32 v49, 31, v48
	v_lshlrev_b64 v[20:21], 12, v[20:21]
	v_lshl_add_u64 v[22:23], v[14:15], 0, v[22:23]
	v_lshlrev_b64 v[24:25], 12, v[24:25]
	v_lshlrev_b64 v[26:27], 12, v[26:27]
	v_lshlrev_b64 v[28:29], 12, v[28:29]
	v_lshlrev_b64 v[30:31], 12, v[30:31]
	v_lshlrev_b64 v[32:33], 12, v[32:33]
	v_lshlrev_b64 v[34:35], 12, v[34:35]
	v_lshlrev_b64 v[36:37], 12, v[36:37]
	v_lshlrev_b64 v[38:39], 12, v[38:39]
	v_lshlrev_b64 v[40:41], 12, v[40:41]
	v_lshlrev_b64 v[42:43], 12, v[42:43]
	v_lshlrev_b64 v[44:45], 12, v[44:45]
	v_lshlrev_b64 v[46:47], 12, v[46:47]
	v_lshlrev_b64 v[48:49], 12, v[48:49]
	v_lshlrev_b64 v[50:51], 12, v[50:51]
	v_lshl_add_u64 v[20:21], v[14:15], 0, v[20:21]
	v_lshl_add_u64 v[26:27], v[14:15], 0, v[26:27]
	v_lshl_add_u64 v[24:25], v[14:15], 0, v[24:25]
	v_lshl_add_u64 v[30:31], v[14:15], 0, v[30:31]
	v_lshl_add_u64 v[28:29], v[14:15], 0, v[28:29]
	v_lshl_add_u64 v[34:35], v[14:15], 0, v[34:35]
	v_lshl_add_u64 v[32:33], v[14:15], 0, v[32:33]
	v_lshl_add_u64 v[38:39], v[14:15], 0, v[38:39]
	v_lshl_add_u64 v[36:37], v[14:15], 0, v[36:37]
	v_lshl_add_u64 v[42:43], v[14:15], 0, v[42:43]
	v_lshl_add_u64 v[40:41], v[14:15], 0, v[40:41]
	v_lshl_add_u64 v[46:47], v[14:15], 0, v[46:47]
	v_lshl_add_u64 v[44:45], v[14:15], 0, v[44:45]
	v_lshl_add_u64 v[50:51], v[14:15], 0, v[50:51]
	v_lshl_add_u64 v[48:49], v[14:15], 0, v[48:49]
	global_load_dword v66, v[22:23], off
	global_load_dword v67, v[20:21], off
	global_load_dword v68, v[26:27], off
	global_load_dword v69, v[24:25], off
	global_load_dword v70, v[30:31], off
	global_load_dword v71, v[28:29], off
	global_load_dword v72, v[34:35], off
	global_load_dword v73, v[32:33], off
	global_load_dword v74, v[38:39], off
	global_load_dword v75, v[36:37], off
	global_load_dword v76, v[42:43], off
	global_load_dword v77, v[40:41], off
	global_load_dword v78, v[46:47], off
	global_load_dword v79, v[44:45], off
	global_load_dword v80, v[50:51], off
	global_load_dword v81, v[48:49], off
	s_add_i32 s25, s25, 16
	s_add_i32 s11, s11, 16
	s_add_i32 s28, s28, -16
	v_mad_u64_u32 v[20:21], s[30:31], v19, s3, v[8:9]
	s_cmp_lg_u32 s28, 0
	v_mad_u64_u32 v[22:23], s[30:31], v4, s3, v[8:9]
	v_mad_u64_u32 v[24:25], s[30:31], v53, s3, v[8:9]
	v_mad_u64_u32 v[26:27], s[30:31], v52, s3, v[8:9]
	v_mad_u64_u32 v[28:29], s[30:31], v55, s3, v[8:9]
	v_mad_u64_u32 v[30:31], s[30:31], v54, s3, v[8:9]
	v_mad_u64_u32 v[32:33], s[30:31], v57, s3, v[8:9]
	v_mad_u64_u32 v[34:35], s[30:31], v56, s3, v[8:9]
	v_mad_u64_u32 v[36:37], s[30:31], v59, s3, v[8:9]
	v_mad_u64_u32 v[38:39], s[30:31], v58, s3, v[8:9]
	v_mad_u64_u32 v[40:41], s[30:31], v61, s3, v[8:9]
	v_mad_u64_u32 v[42:43], s[30:31], v60, s3, v[8:9]
	v_mad_u64_u32 v[44:45], s[30:31], v63, s3, v[8:9]
	v_mad_u64_u32 v[46:47], s[30:31], v62, s3, v[8:9]
	v_mad_u64_u32 v[48:49], s[30:31], v65, s3, v[8:9]
	v_mad_u64_u32 v[50:51], s[30:31], v64, s3, v[8:9]
	s_lshl_b32 s29, s11, 1
	s_lshl_b32 s30, s25, 1
	v_or_b32_e32 v104, s29, v1
	v_or_b32_e32 v119, s30, v2
	s_add_i32 s31, s29, 4
	s_add_i32 s33, s30, 4
	s_add_i32 s34, s29, 8
	s_add_i32 s35, s30, 8
	s_add_i32 s36, s29, 12
	s_add_i32 s37, s30, 12
	s_add_i32 s38, s29, 16
	s_add_i32 s39, s30, 16
	s_add_i32 s40, s29, 20
	s_add_i32 s41, s30, 20
	s_add_i32 s45, s29, 24
	s_add_i32 s47, s30, 24
	s_add_i32 s29, s29, 28
	s_add_i32 s30, s30, 28
	v_add_u32_e32 v122, s10, v119
	v_or_b32_e32 v152, s31, v1
	v_or_b32_e32 v153, s33, v2
	v_or_b32_e32 v154, s34, v1
	v_or_b32_e32 v155, s35, v2
	v_or_b32_e32 v156, s36, v1
	v_or_b32_e32 v157, s37, v2
	v_or_b32_e32 v158, s38, v1
	v_or_b32_e32 v159, s39, v2
	v_or_b32_e32 v160, s40, v1
	v_or_b32_e32 v161, s41, v2
	v_or_b32_e32 v162, s45, v1
	v_or_b32_e32 v163, s47, v2
	v_or_b32_e32 v164, s29, v1
	v_or_b32_e32 v165, s30, v2
	v_add_u32_e32 v120, s22, v104
	v_ashrrev_i32_e32 v123, 31, v122
	v_add_u32_e32 v124, s22, v152
; #define LAS __attribute__((address_space(3)))
; DI void transpose_item(const float* W, int K, int N, bf16_t* WT, int k0, int n0, int drow0, LAS float* scr, int lane) {
; #pragma unroll 8
;     for (int i = 0; i < 32; ++i) { const int kk = 2 * i + (lane >> 5); scr[kk * 33 + (lane & 31)] = W[(size_t)(k0 + kk) * N + n0 + (lane & 31)]; }
;     asm volatile("s_waitcnt lgkmcnt(0)" ::: "memory");
	v_add_u32_e32 v126, s10, v153
	v_add_u32_e32 v128, s22, v154
	v_add_u32_e32 v130, s10, v155
	v_add_u32_e32 v132, s22, v156
	v_add_u32_e32 v134, s10, v157
	v_add_u32_e32 v136, s22, v158
	v_add_u32_e32 v138, s10, v159
	v_add_u32_e32 v140, s22, v160
	v_add_u32_e32 v142, s10, v161
	v_add_u32_e32 v144, s22, v162
	v_add_u32_e32 v146, s10, v163
	v_add_u32_e32 v148, s22, v164
	v_add_u32_e32 v150, s10, v165
	v_ashrrev_i32_e32 v121, 31, v120
	v_lshlrev_b64 v[122:123], 12, v[122:123]
	v_ashrrev_i32_e32 v127, 31, v126
	v_ashrrev_i32_e32 v125, 31, v124
	v_ashrrev_i32_e32 v131, 31, v130
	v_ashrrev_i32_e32 v129, 31, v128
	v_ashrrev_i32_e32 v135, 31, v134
	v_ashrrev_i32_e32 v133, 31, v132
	v_ashrrev_i32_e32 v139, 31, v138
	v_ashrrev_i32_e32 v137, 31, v136
	v_ashrrev_i32_e32 v143, 31, v142
	v_ashrrev_i32_e32 v141, 31, v140
	v_ashrrev_i32_e32 v147, 31, v146
	v_ashrrev_i32_e32 v145, 31, v144
	v_ashrrev_i32_e32 v151, 31, v150
	v_ashrrev_i32_e32 v149, 31, v148
	v_lshlrev_b64 v[120:121], 12, v[120:121]
	v_lshl_add_u64 v[122:123], v[14:15], 0, v[122:123]
	v_lshlrev_b64 v[124:125], 12, v[124:125]
	v_lshlrev_b64 v[126:127], 12, v[126:127]
	v_lshlrev_b64 v[128:129], 12, v[128:129]
	v_lshlrev_b64 v[130:131], 12, v[130:131]
	v_lshlrev_b64 v[132:133], 12, v[132:133]
	v_lshlrev_b64 v[134:135], 12, v[134:135]
	v_lshlrev_b64 v[136:137], 12, v[136:137]
	v_lshlrev_b64 v[138:139], 12, v[138:139]
	v_lshlrev_b64 v[140:141], 12, v[140:141]
	v_lshlrev_b64 v[142:143], 12, v[142:143]
	v_lshlrev_b64 v[144:145], 12, v[144:145]
	v_lshlrev_b64 v[146:147], 12, v[146:147]
	v_lshlrev_b64 v[148:149], 12, v[148:149]
	v_lshlrev_b64 v[150:151], 12, v[150:151]
	v_lshl_add_u64 v[120:121], v[14:15], 0, v[120:121]
	v_lshl_add_u64 v[126:127], v[14:15], 0, v[126:127]
	v_lshl_add_u64 v[124:125], v[14:15], 0, v[124:125]
	v_lshl_add_u64 v[130:131], v[14:15], 0, v[130:131]
	v_lshl_add_u64 v[128:129], v[14:15], 0, v[128:129]
	v_lshl_add_u64 v[134:135], v[14:15], 0, v[134:135]
	v_lshl_add_u64 v[132:133], v[14:15], 0, v[132:133]
	v_lshl_add_u64 v[138:139], v[14:15], 0, v[138:139]
	v_lshl_add_u64 v[136:137], v[14:15], 0, v[136:137]
	v_lshl_add_u64 v[142:143], v[14:15], 0, v[142:143]
	v_lshl_add_u64 v[140:141], v[14:15], 0, v[140:141]
	v_lshl_add_u64 v[146:147], v[14:15], 0, v[146:147]
	v_lshl_add_u64 v[144:145], v[14:15], 0, v[144:145]
	v_lshl_add_u64 v[150:151], v[14:15], 0, v[150:151]
	v_lshl_add_u64 v[148:149], v[14:15], 0, v[148:149]
	global_load_dword v166, v[122:123], off
	global_load_dword v167, v[120:121], off
	global_load_dword v168, v[126:127], off
	global_load_dword v169, v[124:125], off
	global_load_dword v170, v[130:131], off
	global_load_dword v171, v[128:129], off
	global_load_dword v172, v[134:135], off
	global_load_dword v173, v[132:133], off
	global_load_dword v174, v[138:139], off
	global_load_dword v175, v[136:137], off
	global_load_dword v176, v[142:143], off
	global_load_dword v177, v[140:141], off
	global_load_dword v178, v[146:147], off
	global_load_dword v179, v[144:145], off
	global_load_dword v180, v[150:151], off
	global_load_dword v181, v[148:149], off
	s_add_i32 s25, s25, 16
	s_add_i32 s11, s11, 16
	s_add_i32 s28, s28, -16
	v_mad_u64_u32 v[120:121], s[30:31], v119, s3, v[8:9]
	s_cmp_lg_u32 s28, 0
	v_mad_u64_u32 v[122:123], s[30:31], v104, s3, v[8:9]
	v_mad_u64_u32 v[124:125], s[30:31], v153, s3, v[8:9]
	v_mad_u64_u32 v[126:127], s[30:31], v152, s3, v[8:9]
	v_mad_u64_u32 v[128:129], s[30:31], v155, s3, v[8:9]
	v_mad_u64_u32 v[130:131], s[30:31], v154, s3, v[8:9]
	v_mad_u64_u32 v[132:133], s[30:31], v157, s3, v[8:9]
	v_mad_u64_u32 v[134:135], s[30:31], v156, s3, v[8:9]
	v_mad_u64_u32 v[136:137], s[30:31], v159, s3, v[8:9]
	v_mad_u64_u32 v[138:139], s[30:31], v158, s3, v[8:9]
	v_mad_u64_u32 v[140:141], s[30:31], v161, s3, v[8:9]
	v_mad_u64_u32 v[142:143], s[30:31], v160, s3, v[8:9]
	v_mad_u64_u32 v[144:145], s[30:31], v163, s3, v[8:9]
	v_mad_u64_u32 v[146:147], s[30:31], v162, s3, v[8:9]
	v_mad_u64_u32 v[148:149], s[30:31], v165, s3, v[8:9]
	v_mad_u64_u32 v[150:151], s[30:31], v164, s3, v[8:9]
	s_waitcnt vmcnt(31)
; #define LAS __attribute__((address_space(3)))
; DI unsigned pk2(float lo, float hi) { f32x2 v = {lo, hi}; bfv2 b = __builtin_convertvector(v, bfv2); return __builtin_bit_cast(unsigned, b); }
; DI void transpose_item(const float* W, int K, int N, bf16_t* WT, int k0, int n0, int drow0, LAS float* scr, int lane) {
;     ...
;     for (int i = 0; i < 32; ++i) { const int kk = 2 * i + (lane >> 5); scr[kk * 33 + (lane & 31)] = W[(size_t)(k0 + kk) * N + n0 + (lane & 31)]; }
;     asm volatile("s_waitcnt lgkmcnt(0)" ::: "memory");
;     const int c = lane & 7;
; #pragma unroll
;     for (int j = 0; j < 4; ++j) { const int n = (lane >> 3) + 8 * j; const LAS float* s = scr + (8 * c) * 33 + n;
;         u32x4 o; o.x = pk2(s[0 * 33], s[1 * 33]); o.y = pk2(s[2 * 33], s[3 * 33]); o.z = pk2(s[4 * 33], s[5 * 33]); o.w = pk2(s[6 * 33], s[7 * 33]);
;         *(u32x4*)(WT + (size_t)(drow0 + n) * K + k0 + 8 * c) = o; }
;     asm volatile("s_waitcnt lgkmcnt(0)" ::: "memory");
	ds_write_b32 v20, v66
	s_waitcnt vmcnt(30)
	ds_write_b32 v22, v67
	s_waitcnt vmcnt(29)
	ds_write_b32 v24, v68
	s_waitcnt vmcnt(28)
	ds_write_b32 v26, v69
	s_waitcnt vmcnt(27)
	ds_write_b32 v28, v70
	s_waitcnt vmcnt(26)
	ds_write_b32 v30, v71
	s_waitcnt vmcnt(25)
	ds_write_b32 v32, v72
	s_waitcnt vmcnt(24)
	ds_write_b32 v34, v73
	s_waitcnt vmcnt(23)
	ds_write_b32 v36, v74
	s_waitcnt vmcnt(22)
	ds_write_b32 v38, v75
	s_waitcnt vmcnt(21)
	ds_write_b32 v40, v76
	s_waitcnt vmcnt(20)
	ds_write_b32 v42, v77
	s_waitcnt vmcnt(19)
	ds_write_b32 v44, v78
	s_waitcnt vmcnt(18)
	ds_write_b32 v46, v79
	s_waitcnt vmcnt(17)
	ds_write_b32 v48, v80
	s_waitcnt vmcnt(16)
	ds_write_b32 v50, v81
	s_waitcnt vmcnt(15)
	ds_write_b32 v120, v166
	s_waitcnt vmcnt(14)
	ds_write_b32 v122, v167
	s_waitcnt vmcnt(13)
	ds_write_b32 v124, v168
	s_waitcnt vmcnt(12)
	ds_write_b32 v126, v169
	s_waitcnt vmcnt(11)
	ds_write_b32 v128, v170
	s_waitcnt vmcnt(10)
	ds_write_b32 v130, v171
	s_waitcnt vmcnt(9)
	ds_write_b32 v132, v172
	s_waitcnt vmcnt(8)
	ds_write_b32 v134, v173
	s_waitcnt vmcnt(7)
	ds_write_b32 v136, v174
	s_waitcnt vmcnt(6)
	ds_write_b32 v138, v175
	s_waitcnt vmcnt(5)
	ds_write_b32 v140, v176
	s_waitcnt vmcnt(4)
	ds_write_b32 v142, v177
	s_waitcnt vmcnt(3)
	ds_write_b32 v144, v178
	s_waitcnt vmcnt(2)
	ds_write_b32 v146, v179
	s_waitcnt vmcnt(1)
	ds_write_b32 v148, v180
	s_waitcnt vmcnt(0)
	ds_write_b32 v150, v181
	s_waitcnt lgkmcnt(0)
	ds_read2_b32 v[14:15], v9 offset0:33 offset1:41
	ds_read2_b32 v[24:25], v9 offset1:8
	ds_read2_b32 v[26:27], v9 offset0:66 offset1:74
	ds_read2_b32 v[28:29], v9 offset0:99 offset1:107
	ds_read2_b32 v[30:31], v9 offset0:132 offset1:140
	ds_read2_b32 v[32:33], v9 offset0:165 offset1:173
	ds_read2_b32 v[34:35], v9 offset0:198 offset1:206
	ds_read2_b32 v[36:37], v9 offset0:231 offset1:239
	s_addk_i32 s24, 0x1900
	s_mov_b32 s11, s23
	v_or_b32_e32 v4, s24, v3
	v_lshl_add_u64 v[38:39], s[10:11], 1, v[10:11]
	v_lshlrev_b32_e32 v4, 11, v4
	s_waitcnt lgkmcnt(6)
	v_cvt_pk_bf16_f32 v20, v24, v14
	s_waitcnt lgkmcnt(4)
	v_cvt_pk_bf16_f32 v21, v26, v28
	s_waitcnt lgkmcnt(2)
	v_cvt_pk_bf16_f32 v22, v30, v32
	s_waitcnt lgkmcnt(0)
	v_cvt_pk_bf16_f32 v23, v34, v36
	v_lshl_add_u64 v[40:41], v[38:39], 0, v[4:5]
	global_store_dwordx4 v[40:41], v[20:23], off
	v_or_b32_e32 v4, s24, v16
	v_lshlrev_b32_e32 v4, 11, v4
	v_cvt_pk_bf16_f32 v20, v25, v15
	v_cvt_pk_bf16_f32 v21, v27, v29
	v_cvt_pk_bf16_f32 v22, v31, v33
	v_cvt_pk_bf16_f32 v23, v35, v37
	ds_read2_b32 v[24:25], v9 offset0:49 offset1:57
	ds_read2_b32 v[26:27], v9 offset0:16 offset1:24
	ds_read2_b32 v[28:29], v9 offset0:82 offset1:90
	ds_read2_b32 v[30:31], v9 offset0:115 offset1:123
	ds_read2_b32 v[32:33], v9 offset0:148 offset1:156
	ds_read2_b32 v[34:35], v9 offset0:181 offset1:189
	ds_read2_b32 v[36:37], v9 offset0:214 offset1:222
	ds_read2_b32 v[40:41], v9 offset0:247 offset1:255
	v_lshl_add_u64 v[14:15], v[38:39], 0, v[4:5]
	v_or_b32_e32 v4, s24, v17
	v_lshlrev_b32_e32 v4, 11, v4
	global_store_dwordx4 v[14:15], v[20:23], off
	v_lshl_add_u64 v[14:15], v[38:39], 0, v[4:5]
	v_or_b32_e32 v4, s24, v18
	s_waitcnt lgkmcnt(6)
	v_cvt_pk_bf16_f32 v20, v26, v24
	s_waitcnt lgkmcnt(4)
	v_cvt_pk_bf16_f32 v21, v28, v30
	s_waitcnt lgkmcnt(2)
	v_cvt_pk_bf16_f32 v22, v32, v34
	s_waitcnt lgkmcnt(0)
	v_cvt_pk_bf16_f32 v23, v36, v40
	v_lshlrev_b32_e32 v4, 11, v4
	global_store_dwordx4 v[14:15], v[20:23], off
	v_lshl_add_u64 v[14:15], v[38:39], 0, v[4:5]
	s_nop 0
	v_cvt_pk_bf16_f32 v20, v27, v25
	v_cvt_pk_bf16_f32 v21, v29, v31
	v_cvt_pk_bf16_f32 v22, v33, v35
	v_cvt_pk_bf16_f32 v23, v37, v41
	global_store_dwordx4 v[14:15], v[20:23], off
	s_waitcnt lgkmcnt(0)
	s_branch .LBB0_8

; #define LAS __attribute__((address_space(3)))
; DI void transpose_item(const float* W, int K, int N, bf16_t* WT, int k0, int n0, int drow0, LAS float* scr, int lane) {
; #pragma unroll 8
;     for (int i = 0; i < 32; ++i) { const int kk = 2 * i + (lane >> 5); scr[kk * 33 + (lane & 31)] = W[(size_t)(k0 + kk) * N + n0 + (lane & 31)]; }
;     asm volatile("s_waitcnt lgkmcnt(0)" ::: "memory");
.LBB0_15:
	s_lshl_b32 s29, s22, 1
	s_lshl_b32 s30, s25, 1
	v_or_b32_e32 v4, s29, v1
	v_or_b32_e32 v19, s30, v2
	s_add_i32 s31, s29, 4
	s_add_i32 s33, s30, 4
	s_add_i32 s34, s29, 8
	s_add_i32 s35, s30, 8
	s_add_i32 s36, s29, 12
	s_add_i32 s37, s30, 12
	s_add_i32 s38, s29, 16
	s_add_i32 s39, s30, 16
	s_add_i32 s40, s29, 20
	s_add_i32 s41, s30, 20
	s_add_i32 s45, s29, 24
	s_add_i32 s47, s30, 24
	s_add_i32 s29, s29, 28
	s_add_i32 s30, s30, 28
	v_add_u32_e32 v20, s24, v19
	v_or_b32_e32 v52, s31, v1
	v_or_b32_e32 v53, s33, v2
	v_or_b32_e32 v54, s34, v1
	v_or_b32_e32 v55, s35, v2
	v_or_b32_e32 v56, s36, v1
	v_or_b32_e32 v57, s37, v2
	v_or_b32_e32 v58, s38, v1
	v_or_b32_e32 v59, s39, v2
	v_or_b32_e32 v60, s40, v1
	v_or_b32_e32 v61, s41, v2
	v_or_b32_e32 v62, s45, v1
	v_or_b32_e32 v63, s47, v2
	v_or_b32_e32 v64, s29, v1
	v_or_b32_e32 v65, s30, v2
	v_add_u32_e32 v22, s11, v4
	v_mad_i64_i32 v[20:21], s[30:31], v20, s26, v[14:15]
	v_add_u32_e32 v26, s11, v52
	v_add_u32_e32 v24, s24, v53
	v_add_u32_e32 v30, s11, v54
	v_add_u32_e32 v28, s24, v55
	v_add_u32_e32 v34, s11, v56
	v_add_u32_e32 v32, s24, v57
	v_add_u32_e32 v38, s11, v58
	v_add_u32_e32 v36, s24, v59
	v_add_u32_e32 v42, s11, v60
	v_add_u32_e32 v40, s24, v61
	v_add_u32_e32 v46, s11, v62
	v_add_u32_e32 v44, s24, v63
	v_add_u32_e32 v50, s11, v64
	v_add_u32_e32 v48, s24, v65
	v_mad_i64_i32 v[22:23], s[30:31], v22, s26, v[14:15]
	v_mad_i64_i32 v[24:25], s[30:31], v24, s26, v[14:15]
	v_mad_i64_i32 v[26:27], s[30:31], v26, s26, v[14:15]
	v_mad_i64_i32 v[28:29], s[30:31], v28, s26, v[14:15]
	v_mad_i64_i32 v[30:31], s[30:31], v30, s26, v[14:15]
	v_mad_i64_i32 v[32:33], s[30:31], v32, s26, v[14:15]
	v_mad_i64_i32 v[34:35], s[30:31], v34, s26, v[14:15]
	v_mad_i64_i32 v[36:37], s[30:31], v36, s26, v[14:15]
	v_mad_i64_i32 v[38:39], s[30:31], v38, s26, v[14:15]
	v_mad_i64_i32 v[40:41], s[30:31], v40, s26, v[14:15]
	v_mad_i64_i32 v[42:43], s[30:31], v42, s26, v[14:15]
	v_mad_i64_i32 v[44:45], s[30:31], v44, s26, v[14:15]
	v_mad_i64_i32 v[46:47], s[30:31], v46, s26, v[14:15]
	v_mad_i64_i32 v[48:49], s[30:31], v48, s26, v[14:15]
	v_mad_i64_i32 v[50:51], s[30:31], v50, s26, v[14:15]
	global_load_dword v66, v[20:21], off
	global_load_dword v67, v[22:23], off
	global_load_dword v68, v[24:25], off
	global_load_dword v69, v[26:27], off
	global_load_dword v70, v[28:29], off
	global_load_dword v71, v[30:31], off
	global_load_dword v72, v[32:33], off
	global_load_dword v73, v[34:35], off
	global_load_dword v74, v[36:37], off
	global_load_dword v75, v[38:39], off
	global_load_dword v76, v[40:41], off
	global_load_dword v77, v[42:43], off
	global_load_dword v78, v[44:45], off
	global_load_dword v79, v[46:47], off
	global_load_dword v80, v[48:49], off
	global_load_dword v81, v[50:51], off
	s_add_i32 s25, s25, 16
	s_add_i32 s22, s22, 16
	s_add_i32 s28, s28, -16
	v_mad_u64_u32 v[20:21], s[30:31], v19, s3, v[8:9]
	s_cmp_lg_u32 s28, 0
	v_mad_u64_u32 v[22:23], s[30:31], v4, s3, v[8:9]
	v_mad_u64_u32 v[24:25], s[30:31], v53, s3, v[8:9]
	v_mad_u64_u32 v[26:27], s[30:31], v52, s3, v[8:9]
	v_mad_u64_u32 v[28:29], s[30:31], v55, s3, v[8:9]
	v_mad_u64_u32 v[30:31], s[30:31], v54, s3, v[8:9]
	v_mad_u64_u32 v[32:33], s[30:31], v57, s3, v[8:9]
	v_mad_u64_u32 v[34:35], s[30:31], v56, s3, v[8:9]
	v_mad_u64_u32 v[36:37], s[30:31], v59, s3, v[8:9]
	v_mad_u64_u32 v[38:39], s[30:31], v58, s3, v[8:9]
	v_mad_u64_u32 v[40:41], s[30:31], v61, s3, v[8:9]
	v_mad_u64_u32 v[42:43], s[30:31], v60, s3, v[8:9]
	v_mad_u64_u32 v[44:45], s[30:31], v63, s3, v[8:9]
	v_mad_u64_u32 v[46:47], s[30:31], v62, s3, v[8:9]
	v_mad_u64_u32 v[48:49], s[30:31], v65, s3, v[8:9]
	v_mad_u64_u32 v[50:51], s[30:31], v64, s3, v[8:9]
	s_lshl_b32 s29, s22, 1
	s_lshl_b32 s30, s25, 1
	v_or_b32_e32 v104, s29, v1
	v_or_b32_e32 v119, s30, v2
	s_add_i32 s31, s29, 4
	s_add_i32 s33, s30, 4
	s_add_i32 s34, s29, 8
	s_add_i32 s35, s30, 8
	s_add_i32 s36, s29, 12
	s_add_i32 s37, s30, 12
	s_add_i32 s38, s29, 16
	s_add_i32 s39, s30, 16
	s_add_i32 s40, s29, 20
	s_add_i32 s41, s30, 20
	s_add_i32 s45, s29, 24
	s_add_i32 s47, s30, 24
	s_add_i32 s29, s29, 28
	s_add_i32 s30, s30, 28
	v_add_u32_e32 v120, s24, v119
	v_or_b32_e32 v152, s31, v1
	v_or_b32_e32 v153, s33, v2
	v_or_b32_e32 v154, s34, v1
	v_or_b32_e32 v155, s35, v2
	v_or_b32_e32 v156, s36, v1
	v_or_b32_e32 v157, s37, v2
	v_or_b32_e32 v158, s38, v1
	v_or_b32_e32 v159, s39, v2
	v_or_b32_e32 v160, s40, v1
	v_or_b32_e32 v161, s41, v2
	v_or_b32_e32 v162, s45, v1
	v_or_b32_e32 v163, s47, v2
	v_or_b32_e32 v164, s29, v1
	v_or_b32_e32 v165, s30, v2
	v_add_u32_e32 v122, s11, v104
	v_mad_i64_i32 v[120:121], s[30:31], v120, s26, v[14:15]
	v_add_u32_e32 v126, s11, v152
	v_add_u32_e32 v124, s24, v153
	v_add_u32_e32 v130, s11, v154
	v_add_u32_e32 v128, s24, v155
	v_add_u32_e32 v134, s11, v156
	v_add_u32_e32 v132, s24, v157
	v_add_u32_e32 v138, s11, v158
	v_add_u32_e32 v136, s24, v159
	v_add_u32_e32 v142, s11, v160
	v_add_u32_e32 v140, s24, v161
	v_add_u32_e32 v146, s11, v162
	v_add_u32_e32 v144, s24, v163
	v_add_u32_e32 v150, s11, v164
	v_add_u32_e32 v148, s24, v165
	v_mad_i64_i32 v[122:123], s[30:31], v122, s26, v[14:15]
	v_mad_i64_i32 v[124:125], s[30:31], v124, s26, v[14:15]
	v_mad_i64_i32 v[126:127], s[30:31], v126, s26, v[14:15]
	v_mad_i64_i32 v[128:129], s[30:31], v128, s26, v[14:15]
	v_mad_i64_i32 v[130:131], s[30:31], v130, s26, v[14:15]
	v_mad_i64_i32 v[132:133], s[30:31], v132, s26, v[14:15]
	v_mad_i64_i32 v[134:135], s[30:31], v134, s26, v[14:15]
	v_mad_i64_i32 v[136:137], s[30:31], v136, s26, v[14:15]
	v_mad_i64_i32 v[138:139], s[30:31], v138, s26, v[14:15]
	v_mad_i64_i32 v[140:141], s[30:31], v140, s26, v[14:15]
; #define LAS __attribute__((address_space(3)))
; DI unsigned pk2(float lo, float hi) { f32x2 v = {lo, hi}; bfv2 b = __builtin_convertvector(v, bfv2); return __builtin_bit_cast(unsigned, b); }
; DI void transpose_item(const float* W, int K, int N, bf16_t* WT, int k0, int n0, int drow0, LAS float* scr, int lane) {
;     ...
;     for (int i = 0; i < 32; ++i) { const int kk = 2 * i + (lane >> 5); scr[kk * 33 + (lane & 31)] = W[(size_t)(k0 + kk) * N + n0 + (lane & 31)]; }
;     asm volatile("s_waitcnt lgkmcnt(0)" ::: "memory");
;     const int c = lane & 7;
; #pragma unroll
;     for (int j = 0; j < 4; ++j) { const int n = (lane >> 3) + 8 * j; const LAS float* s = scr + (8 * c) * 33 + n;
;         u32x4 o; o.x = pk2(s[0 * 33], s[1 * 33]); o.y = pk2(s[2 * 33], s[3 * 33]); o.z = pk2(s[4 * 33], s[5 * 33]); o.w = pk2(s[6 * 33], s[7 * 33]);
;         *(u32x4*)(WT + (size_t)(drow0 + n) * K + k0 + 8 * c) = o; }
;     asm volatile("s_waitcnt lgkmcnt(0)" ::: "memory");
	v_mad_i64_i32 v[142:143], s[30:31], v142, s26, v[14:15]
	v_mad_i64_i32 v[144:145], s[30:31], v144, s26, v[14:15]
	v_mad_i64_i32 v[146:147], s[30:31], v146, s26, v[14:15]
	v_mad_i64_i32 v[148:149], s[30:31], v148, s26, v[14:15]
	v_mad_i64_i32 v[150:151], s[30:31], v150, s26, v[14:15]
	global_load_dword v166, v[120:121], off
	global_load_dword v167, v[122:123], off
	global_load_dword v168, v[124:125], off
	global_load_dword v169, v[126:127], off
	global_load_dword v170, v[128:129], off
	global_load_dword v171, v[130:131], off
	global_load_dword v172, v[132:133], off
	global_load_dword v173, v[134:135], off
	global_load_dword v174, v[136:137], off
	global_load_dword v175, v[138:139], off
	global_load_dword v176, v[140:141], off
	global_load_dword v177, v[142:143], off
	global_load_dword v178, v[144:145], off
	global_load_dword v179, v[146:147], off
	global_load_dword v180, v[148:149], off
	global_load_dword v181, v[150:151], off
	s_add_i32 s25, s25, 16
	s_add_i32 s22, s22, 16
	s_add_i32 s28, s28, -16
	v_mad_u64_u32 v[120:121], s[30:31], v119, s3, v[8:9]
	s_cmp_lg_u32 s28, 0
	v_mad_u64_u32 v[122:123], s[30:31], v104, s3, v[8:9]
	v_mad_u64_u32 v[124:125], s[30:31], v153, s3, v[8:9]
	v_mad_u64_u32 v[126:127], s[30:31], v152, s3, v[8:9]
	v_mad_u64_u32 v[128:129], s[30:31], v155, s3, v[8:9]
	v_mad_u64_u32 v[130:131], s[30:31], v154, s3, v[8:9]
	v_mad_u64_u32 v[132:133], s[30:31], v157, s3, v[8:9]
	v_mad_u64_u32 v[134:135], s[30:31], v156, s3, v[8:9]
	v_mad_u64_u32 v[136:137], s[30:31], v159, s3, v[8:9]
	v_mad_u64_u32 v[138:139], s[30:31], v158, s3, v[8:9]
	v_mad_u64_u32 v[140:141], s[30:31], v161, s3, v[8:9]
	v_mad_u64_u32 v[142:143], s[30:31], v160, s3, v[8:9]
	v_mad_u64_u32 v[144:145], s[30:31], v163, s3, v[8:9]
	v_mad_u64_u32 v[146:147], s[30:31], v162, s3, v[8:9]
	v_mad_u64_u32 v[148:149], s[30:31], v165, s3, v[8:9]
	v_mad_u64_u32 v[150:151], s[30:31], v164, s3, v[8:9]
	s_waitcnt vmcnt(31)
	ds_write_b32 v20, v66
	s_waitcnt vmcnt(30)
	ds_write_b32 v22, v67
	s_waitcnt vmcnt(29)
	ds_write_b32 v24, v68
	s_waitcnt vmcnt(28)
	ds_write_b32 v26, v69
	s_waitcnt vmcnt(27)
	ds_write_b32 v28, v70
	s_waitcnt vmcnt(26)
	ds_write_b32 v30, v71
	s_waitcnt vmcnt(25)
	ds_write_b32 v32, v72
	s_waitcnt vmcnt(24)
	ds_write_b32 v34, v73
	s_waitcnt vmcnt(23)
	ds_write_b32 v36, v74
	s_waitcnt vmcnt(22)
	ds_write_b32 v38, v75
	s_waitcnt vmcnt(21)
	ds_write_b32 v40, v76
	s_waitcnt vmcnt(20)
	ds_write_b32 v42, v77
	s_waitcnt vmcnt(19)
	ds_write_b32 v44, v78
	s_waitcnt vmcnt(18)
	ds_write_b32 v46, v79
	s_waitcnt vmcnt(17)
	ds_write_b32 v48, v80
	s_waitcnt vmcnt(16)
	ds_write_b32 v50, v81
	s_waitcnt vmcnt(15)
	ds_write_b32 v120, v166
	s_waitcnt vmcnt(14)
	ds_write_b32 v122, v167
	s_waitcnt vmcnt(13)
	ds_write_b32 v124, v168
	s_waitcnt vmcnt(12)
	ds_write_b32 v126, v169
	s_waitcnt vmcnt(11)
	ds_write_b32 v128, v170
	s_waitcnt vmcnt(10)
	ds_write_b32 v130, v171
	s_waitcnt vmcnt(9)
	ds_write_b32 v132, v172
	s_waitcnt vmcnt(8)
	ds_write_b32 v134, v173
	s_waitcnt vmcnt(7)
	ds_write_b32 v136, v174
	s_waitcnt vmcnt(6)
	ds_write_b32 v138, v175
	s_waitcnt vmcnt(5)
	ds_write_b32 v140, v176
	s_waitcnt vmcnt(4)
	ds_write_b32 v142, v177
	s_waitcnt vmcnt(3)
	ds_write_b32 v144, v178
	s_waitcnt vmcnt(2)
	ds_write_b32 v146, v179
	s_waitcnt vmcnt(1)
	ds_write_b32 v148, v180
	s_waitcnt vmcnt(0)
	ds_write_b32 v150, v181
	s_waitcnt lgkmcnt(0)
	ds_read2_b32 v[14:15], v9 offset0:33 offset1:41
	ds_read2_b32 v[24:25], v9 offset1:8
	ds_read2_b32 v[26:27], v9 offset0:66 offset1:74
	ds_read2_b32 v[28:29], v9 offset0:99 offset1:107
	ds_read2_b32 v[30:31], v9 offset0:132 offset1:140
	ds_read2_b32 v[32:33], v9 offset0:165 offset1:173
	ds_read2_b32 v[34:35], v9 offset0:198 offset1:206
	ds_read2_b32 v[36:37], v9 offset0:231 offset1:239
	v_or_b32_e32 v40, s10, v3
	s_ashr_i32 s25, s24, 31
	v_ashrrev_i32_e32 v41, 31, v40
	v_lshl_add_u64 v[38:39], s[24:25], 1, v[10:11]
	v_lshlrev_b64 v[40:41], 11, v[40:41]
	s_waitcnt lgkmcnt(6)
	v_cvt_pk_bf16_f32 v20, v24, v14
	s_waitcnt lgkmcnt(4)
	v_cvt_pk_bf16_f32 v21, v26, v28
	s_waitcnt lgkmcnt(2)
	v_cvt_pk_bf16_f32 v22, v30, v32
	s_waitcnt lgkmcnt(0)
	v_cvt_pk_bf16_f32 v23, v34, v36
	v_lshl_add_u64 v[40:41], v[38:39], 0, v[40:41]
	v_or_b32_e32 v14, s10, v16
	global_store_dwordx4 v[40:41], v[20:23], off
	s_nop 1
	v_cvt_pk_bf16_f32 v20, v25, v15
	v_ashrrev_i32_e32 v15, 31, v14
	v_cvt_pk_bf16_f32 v21, v27, v29
	v_cvt_pk_bf16_f32 v22, v31, v33
	v_cvt_pk_bf16_f32 v23, v35, v37
	v_lshlrev_b64 v[14:15], 11, v[14:15]
	ds_read2_b32 v[24:25], v9 offset0:49 offset1:57
	ds_read2_b32 v[26:27], v9 offset0:16 offset1:24
	ds_read2_b32 v[28:29], v9 offset0:82 offset1:90
	ds_read2_b32 v[30:31], v9 offset0:115 offset1:123
	ds_read2_b32 v[32:33], v9 offset0:148 offset1:156
	ds_read2_b32 v[34:35], v9 offset0:181 offset1:189
	ds_read2_b32 v[36:37], v9 offset0:214 offset1:222
	ds_read2_b32 v[40:41], v9 offset0:247 offset1:255
	v_lshl_add_u64 v[14:15], v[38:39], 0, v[14:15]
	global_store_dwordx4 v[14:15], v[20:23], off
	v_or_b32_e32 v14, s10, v17
	v_ashrrev_i32_e32 v15, 31, v14
	v_lshlrev_b64 v[14:15], 11, v[14:15]
	s_waitcnt lgkmcnt(6)
	v_cvt_pk_bf16_f32 v20, v26, v24
	s_waitcnt lgkmcnt(4)
	v_cvt_pk_bf16_f32 v21, v28, v30
	s_waitcnt lgkmcnt(2)
	v_cvt_pk_bf16_f32 v22, v32, v34
	s_waitcnt lgkmcnt(0)
	v_cvt_pk_bf16_f32 v23, v36, v40
	v_lshl_add_u64 v[14:15], v[38:39], 0, v[14:15]
	global_store_dwordx4 v[14:15], v[20:23], off
	v_or_b32_e32 v14, s10, v18
	v_ashrrev_i32_e32 v15, 31, v14
	v_lshlrev_b64 v[14:15], 11, v[14:15]
	v_cvt_pk_bf16_f32 v20, v27, v25
	v_cvt_pk_bf16_f32 v21, v29, v31
	v_cvt_pk_bf16_f32 v22, v33, v35
	v_cvt_pk_bf16_f32 v23, v37, v41
	v_lshl_add_u64 v[14:15], v[38:39], 0, v[14:15]
	global_store_dwordx4 v[14:15], v[20:23], off
	s_waitcnt lgkmcnt(0)
	s_branch .LBB0_8
